# MoBA gated past blocks: per-query select bit applied with one compare and 16 selects instead of the generic 3-mode per-element mask code
# speedup vs baseline: 1.0098x; 1.0060x over previous
; template <int DQ, int TYPE>
; __device__ __forceinline__ void attn_item(PP p, int layer, int b, int h, int qt, char* lds, const int tid_, unsigned* next_ctr, volatile XLAS unsigned* slot) {
;     ...
;         if (!skip) {
;             const bf16_t* Ks = (const bf16_t*)(lds + buf * STAGE); const bf16_t* Vt = (const bf16_t*)(lds + buf * STAGE + KBYTES);
;             f32x16 sacc;
; #pragma unroll
;             for (int i = 0; i < 16; ++i) sacc[i] = 0.f;
;             const bf16_t* kb_ = Ks + (32 * kh + r) * KLD + 8 * hh;
;             bf16x8 kf[2][GK];
; #pragma unroll
;             for (int i = 0; i < GK; ++i) kf[0][i] = *(const bf16x8*)(kb_ + 16 * i);
; #pragma unroll
;             for (int g = 0; g < NG; ++g) {
;                 if (g + 1 < NG) {
; #pragma unroll
;                     for (int i = 0; i < GK; ++i) kf[(g + 1) & 1][i] = *(const bf16x8*)(kb_ + 16 * ((g + 1) * GK + i));
;                 }
;                 __builtin_amdgcn_sched_barrier(0);
; #pragma unroll
;                 for (int i = 0; i < GK; ++i) sacc = __builtin_amdgcn_mfma_f32_32x32x16_bf16(kf[g & 1][i], qf[g * GK + i], sacc, 0, 0, 0);
;                 __builtin_amdgcn_sched_barrier(0);
;             }
;             const bf16_t* vb0 = Vt + r * VLD + 32 * kh + 4 * hh;
;             u32x2 vf[2][4][2];
; #pragma unroll
;             for (int md = 0; md < 4; ++md) { vf[0][md][0] = *(const u32x2*)(vb0 + md * 32 * VLD); vf[0][md][1] = *(const u32x2*)(vb0 + md * 32 * VLD + 8); }
;             if (mode != 0) {
;                 const bool selbit = (qmask >> (j >> 2)) & 1u;
; #pragma unroll
;                 for (int i = 0; i < 16; ++i) {
;                     const int kpos = kbase_pos + 8 * (i >> 2) + 4 * hh + (i & 3);
;                     const int dd = qpos - kpos;
;                     bool ok;
;                     if (mode == 1) ok = dd >= 0; else if (mode == 2) ok = (dd >= 0 && dd < 128); else ok = selbit;
;                     if (!ok) sacc[i] = -INFINITY;
;                 }
.LBB0_640:
	s_and_b32 s63, s61, 1
	s_lshr_b32 s64, s61, 2
	s_cmp_ge_u32 s64, s94
	s_cselect_b64 s[14:15], -1, 0
	s_cmp_lt_u32 s61, s57
	s_cselect_b64 s[16:17], -1, 0
	s_cmp_ge_u32 s61, s57
	s_cselect_b64 s[50:51], -1, 0
	s_and_b64 s[50:51], s[14:15], s[50:51]
	s_cmp_gt_i32 s62, s59
	s_cselect_b64 s[66:67], -1, 0
	s_and_b64 s[66:67], s[50:51], s[66:67]
	s_and_b64 vcc, exec, s[66:67]
	s_cbranch_vccnz .LBB0_646
	s_and_b64 s[14:15], s[14:15], s[16:17]
	s_mul_i32 s16, s63, 0x8f70
	s_add_i32 s16, s16, 16
	v_lshlrev_b32_e32 v66, 1, v153
	v_add3_u32 v70, s16, v162, v66
	ds_read_b128 v[66:69], v70
	ds_read_b128 v[130:133], v70 offset:32
	ds_read_b128 v[134:137], v70 offset:64
	ds_read_b128 v[138:141], v70 offset:96
	ds_read_b128 v[142:145], v70 offset:128
	ds_read_b128 v[172:175], v70 offset:160
	ds_read_b128 v[190:193], v70 offset:192
	ds_read_b128 v[194:197], v70 offset:224
	s_waitcnt lgkmcnt(7)
	v_mfma_f32_32x32x16_bf16 v[66:81], v[66:69], v[90:93], 0
	s_waitcnt lgkmcnt(6)
	v_mfma_f32_32x32x16_bf16 v[66:81], v[130:133], v[94:97], v[66:81]
	s_waitcnt lgkmcnt(5)
	v_mfma_f32_32x32x16_bf16 v[66:81], v[134:137], v[98:101], v[66:81]
	s_waitcnt lgkmcnt(4)
	v_mfma_f32_32x32x16_bf16 v[66:81], v[138:141], v[102:105], v[66:81]
	s_waitcnt lgkmcnt(3)
	v_mfma_f32_32x32x16_bf16 v[66:81], v[142:145], v[110:113], v[66:81]
	s_lshl_b32 s17, s58, 1
	s_add_i32 s17, s17, s16
	v_lshlrev_b32_e32 v130, 1, v147
	v_add3_u32 v130, s17, v163, v130
	s_and_b64 vcc, exec, s[14:15]
	s_waitcnt lgkmcnt(2)
	v_mfma_f32_32x32x16_bf16 v[66:81], v[172:175], v[114:117], v[66:81]
	v_add_u32_e32 v173, 0x4000, v130
	v_add_u32_e32 v175, 0x4120, v130
	v_add_u32_e32 v174, 0x4240, v130
	v_add_u32_e32 v172, 0x4360, v130
	ds_read2_b64 v[142:145], v173 offset0:128 offset1:130
	ds_read2_b64 v[138:141], v175 offset0:160 offset1:162
	ds_read2_b64 v[134:137], v174 offset0:192 offset1:194
	s_waitcnt lgkmcnt(4)
	v_mfma_f32_32x32x16_bf16 v[66:81], v[190:193], v[122:125], v[66:81]
	ds_read2_b64 v[130:133], v172 offset0:224 offset1:226
	s_waitcnt lgkmcnt(4)
	v_mfma_f32_32x32x16_bf16 v[66:81], v[194:197], v[126:129], v[66:81]
	s_cbranch_vccnz .LBB0_643
	s_cmp_eq_u64 s[50:51], 0
	s_cbranch_scc0 .Lmoba_mask_slow
	v_lshrrev_b32_e32 v152, s64, v157
	v_and_b32_e32 v152, 1, v152
	v_cmp_eq_u32_e32 vcc, 1, v152
	s_nop 5
	v_cndmask_b32_e32 v66, v225, v66, vcc
	v_cndmask_b32_e32 v67, v225, v67, vcc
	v_cndmask_b32_e32 v68, v225, v68, vcc
	v_cndmask_b32_e32 v69, v225, v69, vcc
	v_cndmask_b32_e32 v70, v225, v70, vcc
	v_cndmask_b32_e32 v71, v225, v71, vcc
	v_cndmask_b32_e32 v72, v225, v72, vcc
	v_cndmask_b32_e32 v73, v225, v73, vcc
	v_cndmask_b32_e32 v74, v225, v74, vcc
	v_cndmask_b32_e32 v75, v225, v75, vcc
	v_cndmask_b32_e32 v76, v225, v76, vcc
	v_cndmask_b32_e32 v77, v225, v77, vcc
	v_cndmask_b32_e32 v78, v225, v78, vcc
	v_cndmask_b32_e32 v79, v225, v79, vcc
	v_cndmask_b32_e32 v80, v225, v80, vcc
	v_cndmask_b32_e32 v81, v225, v81, vcc
	s_branch .Lmoba_after_nop
; template <int DQ, int TYPE>
; __device__ __forceinline__ void attn_item(PP p, int layer, int b, int h, int qt, char* lds, const int tid_, unsigned* next_ctr, volatile XLAS unsigned* slot) {
;     ...
;             if (mode != 0) {
;                 const bool selbit = (qmask >> (j >> 2)) & 1u;
; #pragma unroll
;                 for (int i = 0; i < 16; ++i) {
;                     const int kpos = kbase_pos + 8 * (i >> 2) + 4 * hh + (i & 3);
;                     const int dd = qpos - kpos;
;                     bool ok;
;                     if (mode == 1) ok = dd >= 0; else if (mode == 2) ok = (dd >= 0 && dd < 128); else ok = selbit;
;                     if (!ok) sacc[i] = -INFINITY;
;                 }
;             }
.Lmoba_mask_slow:
	v_add_u32_e32 v165, s62, v147
	v_cmp_ge_i32_e32 vcc, v0, v165
	v_lshrrev_b32_e32 v152, s64, v157
	s_nop 0
	v_cndmask_b32_e64 v177, 0, 1, vcc
	v_cndmask_b32_e64 v177, v152, v177, s[50:51]
	v_and_b32_e32 v177, 1, v177
	v_cmp_eq_u32_e32 vcc, 1, v177
	s_nop 2
	v_cndmask_b32_e32 v66, v225, v66, vcc
	v_cmp_gt_i32_e32 vcc, v0, v165
	s_nop 1
	v_cndmask_b32_e64 v177, 0, 1, vcc
	v_cndmask_b32_e64 v177, v152, v177, s[50:51]
	v_and_b32_e32 v177, 1, v177
	v_cmp_eq_u32_e32 vcc, 1, v177
	v_add_u32_e32 v177, 2, v165
	s_nop 0
	v_cndmask_b32_e32 v67, v225, v67, vcc
	v_cmp_ge_i32_e32 vcc, v0, v177
	s_nop 1
	v_cndmask_b32_e64 v177, 0, 1, vcc
	v_cndmask_b32_e64 v177, v152, v177, s[50:51]
	v_and_b32_e32 v177, 1, v177
	v_cmp_eq_u32_e32 vcc, 1, v177
	v_add_u32_e32 v177, 3, v165
	s_nop 0
	v_cndmask_b32_e32 v68, v225, v68, vcc
	v_cmp_ge_i32_e32 vcc, v0, v177
	s_nop 1
	v_cndmask_b32_e64 v177, 0, 1, vcc
	v_cndmask_b32_e64 v177, v152, v177, s[50:51]
	v_and_b32_e32 v177, 1, v177
	v_cmp_eq_u32_e32 vcc, 1, v177
	v_add_u32_e32 v177, 8, v165
	s_nop 0
	v_cndmask_b32_e32 v69, v225, v69, vcc
	v_cmp_ge_i32_e32 vcc, v0, v177
	s_nop 1
	v_cndmask_b32_e64 v177, 0, 1, vcc
	v_cndmask_b32_e64 v177, v152, v177, s[50:51]
	v_and_b32_e32 v177, 1, v177
	v_cmp_eq_u32_e32 vcc, 1, v177
	v_add_u32_e32 v177, 9, v165
	s_nop 0
	v_cndmask_b32_e32 v70, v225, v70, vcc
	v_cmp_ge_i32_e32 vcc, v0, v177
	s_nop 1
	v_cndmask_b32_e64 v177, 0, 1, vcc
	v_cndmask_b32_e64 v177, v152, v177, s[50:51]
	v_and_b32_e32 v177, 1, v177
	v_cmp_eq_u32_e32 vcc, 1, v177
	v_add_u32_e32 v177, 10, v165
	s_nop 0
	v_cndmask_b32_e32 v71, v225, v71, vcc
	v_cmp_ge_i32_e32 vcc, v0, v177
	s_nop 1
	v_cndmask_b32_e64 v177, 0, 1, vcc
	v_cndmask_b32_e64 v177, v152, v177, s[50:51]
	v_and_b32_e32 v177, 1, v177
	v_cmp_eq_u32_e32 vcc, 1, v177
	v_add_u32_e32 v177, 11, v165
	s_nop 0
	v_cndmask_b32_e32 v72, v225, v72, vcc
	v_cmp_ge_i32_e32 vcc, v0, v177
	s_nop 1
	v_cndmask_b32_e64 v177, 0, 1, vcc
	v_cndmask_b32_e64 v177, v152, v177, s[50:51]
	v_and_b32_e32 v177, 1, v177
	v_cmp_eq_u32_e32 vcc, 1, v177
	v_add_u32_e32 v177, 16, v165
	s_nop 0
	v_cndmask_b32_e32 v73, v225, v73, vcc
	v_cmp_ge_i32_e32 vcc, v0, v177
	s_nop 1
	v_cndmask_b32_e64 v177, 0, 1, vcc
	v_cndmask_b32_e64 v177, v152, v177, s[50:51]
	v_and_b32_e32 v177, 1, v177
	v_cmp_eq_u32_e32 vcc, 1, v177
	v_add_u32_e32 v177, 17, v165
	s_nop 0
	v_cndmask_b32_e32 v74, v225, v74, vcc
	v_cmp_ge_i32_e32 vcc, v0, v177
	s_nop 1
	v_cndmask_b32_e64 v177, 0, 1, vcc
	v_cndmask_b32_e64 v177, v152, v177, s[50:51]
	v_and_b32_e32 v177, 1, v177
	v_cmp_eq_u32_e32 vcc, 1, v177
	v_add_u32_e32 v177, 18, v165
	s_nop 0
	v_cndmask_b32_e32 v75, v225, v75, vcc
	v_cmp_ge_i32_e32 vcc, v0, v177
	s_nop 1
	v_cndmask_b32_e64 v177, 0, 1, vcc
	v_cndmask_b32_e64 v177, v152, v177, s[50:51]
	v_and_b32_e32 v177, 1, v177
	v_cmp_eq_u32_e32 vcc, 1, v177
	v_add_u32_e32 v177, 19, v165
	s_nop 0
	v_cndmask_b32_e32 v76, v225, v76, vcc
	v_cmp_ge_i32_e32 vcc, v0, v177
	s_nop 1
	v_cndmask_b32_e64 v177, 0, 1, vcc
	v_cndmask_b32_e64 v177, v152, v177, s[50:51]
	v_and_b32_e32 v177, 1, v177
	v_cmp_eq_u32_e32 vcc, 1, v177
	v_add_u32_e32 v177, 24, v165
	s_nop 0
	v_cndmask_b32_e32 v77, v225, v77, vcc
	v_cmp_ge_i32_e32 vcc, v0, v177
	s_nop 1
	v_cndmask_b32_e64 v177, 0, 1, vcc
	v_cndmask_b32_e64 v177, v152, v177, s[50:51]
	v_and_b32_e32 v177, 1, v177
	v_cmp_eq_u32_e32 vcc, 1, v177
	v_add_u32_e32 v177, 25, v165
	s_nop 0
	v_cndmask_b32_e32 v78, v225, v78, vcc
	v_cmp_ge_i32_e32 vcc, v0, v177
	s_nop 1
	v_cndmask_b32_e64 v177, 0, 1, vcc
	v_cndmask_b32_e64 v177, v152, v177, s[50:51]
	v_and_b32_e32 v177, 1, v177
	v_cmp_eq_u32_e32 vcc, 1, v177
	v_add_u32_e32 v177, 26, v165
	v_add_u32_e32 v165, 27, v165
	v_cndmask_b32_e32 v79, v225, v79, vcc
	v_cmp_ge_i32_e32 vcc, v0, v177
	s_nop 1
	v_cndmask_b32_e64 v177, 0, 1, vcc
	v_cndmask_b32_e64 v177, v152, v177, s[50:51]
	v_and_b32_e32 v177, 1, v177
	v_cmp_eq_u32_e32 vcc, 1, v177
	s_nop 1
	v_cndmask_b32_e32 v80, v225, v80, vcc
	v_cmp_ge_i32_e32 vcc, v0, v165
	s_nop 1
	v_cndmask_b32_e64 v165, 0, 1, vcc
	v_cndmask_b32_e64 v152, v152, v165, s[50:51]
	v_and_b32_e32 v152, 1, v152
	v_cmp_eq_u32_e32 vcc, 1, v152
	s_nop 1
	v_cndmask_b32_e32 v81, v225, v81, vcc

; __device__ __forceinline__ float fast_exp2(float x) { return __builtin_amdgcn_exp2f(x); }
; template <int DQ, int TYPE>
; __device__ __forceinline__ void attn_item(PP p, int layer, int b, int h, int qt, char* lds, const int tid_, unsigned* next_ctr, volatile XLAS unsigned* slot) {
;     ...
;             float mx = fmaxf(sacc[0], sacc[1]);
; #pragma unroll
;             for (int i = 2; i < 16; i += 2) mx = fmaxf(mx, fmaxf(sacc[i], sacc[i + 1]));
;             mx *= c;
;             mx = fmaxf(mx, __shfl_xor(mx, 32));
;             const float m_old_ = m_run;
;             const float mnew = fmaxf(m_run, mx);
;             const float alpha = fast_exp2(m_run - mnew);
;             m_run = mnew;
;             float ls = 0.f;
; #pragma unroll
;             for (int i = 0; i < 16; ++i) { sacc[i] = fast_exp2(__builtin_fmaf(sacc[i], c, -mnew)); ls += sacc[i]; }
;             l_run = l_run * alpha + ls;
;             if (__builtin_amdgcn_ballot_w64(mx > m_old_) != 0) {
; #pragma unroll
;                 for (int md = 0; md < 4; ++md) O[md] *= alpha;
;             }
.Lmoba_after_nop:
	v_max3_f32 v152, v66, v67, v68
	v_max3_f32 v165, v69, v70, v71
	v_max3_f32 v177, v72, v73, v74
	v_max3_f32 v187, v75, v76, v77
	v_max3_f32 v152, v152, v78, v79
	v_max3_f32 v165, v165, v80, v81
	v_max3_f32 v152, v152, v177, v187
	v_max_f32_e32 v152, v152, v165
	v_mul_f32_e32 v152, 0x3e0293ee, v152
	v_mov_b32_e32 v165, v152
	s_nop 1
	v_permlane32_swap_b32_e32 v165, v152
	v_max_f32_e32 v177, v152, v165
	v_add_f32_e32 v152, 0x41000000, v176
	v_cmp_gt_f32_e32 vcc, v177, v152
	s_nop 1
	v_cndmask_b32_e32 v165, v176, v177, vcc
	v_sub_f32_e32 v152, v176, v165
	v_exp_f32_e32 v152, v152
	s_cbranch_vccz .LBB0_645
	v_pk_mul_f32 v[32:33], v[32:33], v[152:153] op_sel_hi:[1,0]
	v_pk_mul_f32 v[30:31], v[30:31], v[152:153] op_sel_hi:[1,0]
	v_pk_mul_f32 v[28:29], v[28:29], v[152:153] op_sel_hi:[1,0]
	v_pk_mul_f32 v[26:27], v[26:27], v[152:153] op_sel_hi:[1,0]
	v_pk_mul_f32 v[24:25], v[24:25], v[152:153] op_sel_hi:[1,0]
	v_pk_mul_f32 v[22:23], v[22:23], v[152:153] op_sel_hi:[1,0]
	v_pk_mul_f32 v[20:21], v[20:21], v[152:153] op_sel_hi:[1,0]
	v_pk_mul_f32 v[18:19], v[18:19], v[152:153] op_sel_hi:[1,0]
	v_pk_mul_f32 v[16:17], v[16:17], v[152:153] op_sel_hi:[1,0]
	v_pk_mul_f32 v[14:15], v[14:15], v[152:153] op_sel_hi:[1,0]
	v_pk_mul_f32 v[12:13], v[12:13], v[152:153] op_sel_hi:[1,0]
	v_pk_mul_f32 v[10:11], v[10:11], v[152:153] op_sel_hi:[1,0]
	v_pk_mul_f32 v[8:9], v[8:9], v[152:153] op_sel_hi:[1,0]
	v_pk_mul_f32 v[6:7], v[6:7], v[152:153] op_sel_hi:[1,0]
	v_pk_mul_f32 v[4:5], v[4:5], v[152:153] op_sel_hi:[1,0]
	v_pk_mul_f32 v[2:3], v[2:3], v[152:153] op_sel_hi:[1,0]
	v_pk_mul_f32 v[64:65], v[64:65], v[152:153] op_sel_hi:[1,0]
	v_pk_mul_f32 v[62:63], v[62:63], v[152:153] op_sel_hi:[1,0]
	v_pk_mul_f32 v[60:61], v[60:61], v[152:153] op_sel_hi:[1,0]
	v_pk_mul_f32 v[58:59], v[58:59], v[152:153] op_sel_hi:[1,0]
	v_pk_mul_f32 v[56:57], v[56:57], v[152:153] op_sel_hi:[1,0]
	v_pk_mul_f32 v[54:55], v[54:55], v[152:153] op_sel_hi:[1,0]
	v_pk_mul_f32 v[52:53], v[52:53], v[152:153] op_sel_hi:[1,0]
	v_pk_mul_f32 v[50:51], v[50:51], v[152:153] op_sel_hi:[1,0]
	v_pk_mul_f32 v[48:49], v[48:49], v[152:153] op_sel_hi:[1,0]
	v_pk_mul_f32 v[46:47], v[46:47], v[152:153] op_sel_hi:[1,0]
	v_pk_mul_f32 v[44:45], v[44:45], v[152:153] op_sel_hi:[1,0]
	v_pk_mul_f32 v[42:43], v[42:43], v[152:153] op_sel_hi:[1,0]
	v_pk_mul_f32 v[40:41], v[40:41], v[152:153] op_sel_hi:[1,0]
	v_pk_mul_f32 v[38:39], v[38:39], v[152:153] op_sel_hi:[1,0]
	v_pk_mul_f32 v[36:37], v[36:37], v[152:153] op_sel_hi:[1,0]
	v_pk_mul_f32 v[34:35], v[34:35], v[152:153] op_sel_hi:[1,0]
